# s5_gen: first-section loads in one batch, C table by waves 4-7 in one batch, hand-written Bst rows
# speedup vs baseline: 1.0111x; 1.0056x over previous
; __device__ __forceinline__ void s5_gen(LAS unsigned char* lds, const S5In P, int g, int q, bf16_t* Bst, bf16_t* Bout, const int tid) {
;     ...
;     if (tid < 128) {
;         const int di = tid >> 6, p = tid & 63, gp = (di * 64 + g) * 64 + p;
;         const float dt = __builtin_amdgcn_exp2f(P.log_dt[di * 64 + g] * 1.4426950408889634f);
;         const float lr = P.lam_re[gp], li = P.lam_im[gp];
;         const float mag = __builtin_amdgcn_exp2f(lr * dt * 1.4426950408889634f), frv = __builtin_amdgcn_fractf(li * dt * 0.15915494309189535f);
;         const float ar = mag * __builtin_amdgcn_cosf(frv), ai = mag * __builtin_amdgcn_sinf(frv);
;         const float nr = ar - 1.0f, ni = ai, den = lr * lr + li * li;
;         const float fr = (nr * lr + ni * li) / den, fi = (ni * lr - nr * li) / den;
;         float wr = 1.0f, wi = 0.0f;
;         for (int k = 0; k <= 16; ++k) { pw[(di * 64 + p) * 17 + k] = (f32x2v){wr, wi}; const float t = wr * ar - wi * ai; wi = wr * ai + wi * ar; wr = t; }
.LBB0_192:
	s_ashr_i32 s16, s53, 2
	s_and_saveexec_b64 s[28:29], s[36:37]
	s_cbranch_execz .LBB0_194
	v_add_u32_e32 v0, s16, v34
	v_ashrrev_i32_e32 v1, 31, v0
	v_lshl_or_b32 v2, v0, 6, v64
	v_lshl_add_u64 v[0:1], v[0:1], 2, s[0:1]
	global_load_dword v43, v[0:1], off
	v_ashrrev_i32_e32 v3, 31, v2
	v_lshlrev_b64 v[0:1], 2, v[2:3]
	v_lshl_add_u64 v[4:5], s[12:13], 0, v[0:1]
	v_lshl_add_u64 v[0:1], s[14:15], 0, v[0:1]
	global_load_dword v32, v[4:5], off
	global_load_dword v33, v[0:1], off
	v_lshlrev_b64 v[0:1], 6, v[2:3]
	v_lshl_add_u64 v[4:5], s[2:3], 0, v[0:1]
	v_lshl_add_u64 v[28:29], s[26:27], 0, v[0:1]
	global_load_dwordx4 v[0:3], v[4:5], off offset:48
	global_load_dwordx4 v[8:11], v[4:5], off offset:32
	global_load_dwordx4 v[12:15], v[4:5], off offset:16
	global_load_dwordx4 v[16:19], v[4:5], off
	s_nop 0
	global_load_dwordx4 v[4:7], v[28:29], off offset:48
	global_load_dwordx4 v[20:23], v[28:29], off offset:32
	global_load_dwordx4 v[24:27], v[28:29], off offset:16
	s_nop 0
	global_load_dwordx4 v[28:31], v[28:29], off
	v_mov_b32_e32 v211, v209
	s_waitcnt vmcnt(0)
	v_mul_f32_e32 v43, 0x3fb8aa3b, v43
	v_exp_f32_e32 v43, v43
	s_nop 0
	s_waitcnt vmcnt(9)
	v_mov_b32_e32 v53, v32
	v_mul_f32_e32 v47, v32, v43
	s_waitcnt vmcnt(8)
	v_mul_f32_e32 v43, v33, v43
	v_mul_f32_e32 v43, 0.15915494, v43
	v_mul_f32_e32 v47, 0x3fb8aa3b, v47
	v_fract_f32_e32 v43, v43
	v_exp_f32_e32 v48, v47
	v_cos_f32_e32 v50, v43
	v_sin_f32_e32 v51, v43
	v_pk_mul_f32 v[44:45], v[32:33], v[32:33]
	v_mov_b32_e32 v46, v33
	v_mov_b32_e32 v52, v33
	v_pk_add_f32 v[32:33], v[44:45], v[44:45] op_sel:[0,1] op_sel_hi:[0,1]
	v_pk_mul_f32 v[44:45], v[48:49], v[50:51] op_sel_hi:[0,1]
	v_pk_mul_f32 v[56:57], v[44:45], 0 op_sel_hi:[1,0]
	v_add_f32_e32 v54, -1.0, v44
	v_pk_fma_f32 v[58:59], v[48:49], v[50:51], v[56:57] op_sel:[0,0,1] op_sel_hi:[0,1,0] neg_lo:[0,0,1] neg_hi:[0,0,1]
	v_pk_fma_f32 v[48:49], v[48:49], v[50:51], v[56:57] op_sel:[0,0,1] op_sel_hi:[0,1,0]
	v_pk_mul_f32 v[50:51], v[52:53], v[54:55] op_sel:[1,0] op_sel_hi:[0,0]
	v_mov_b32_e32 v48, v58
	v_mov_b32_e32 v54, v58
	v_mov_b32_e32 v55, v49
	v_pk_fma_f32 v[46:47], v[46:47], v[44:45], v[50:51] op_sel:[0,1,0]
	v_pk_fma_f32 v[50:51], v[52:53], v[44:45], v[50:51] op_sel:[0,1,0] neg_lo:[0,0,1] neg_hi:[0,0,1]
	v_pk_mul_f32 v[52:53], v[44:45], v[48:49] op_sel:[1,0]
	ds_write2_b64 v40, v[210:211], v[54:55] offset1:1
	v_pk_fma_f32 v[54:55], v[44:45], v[58:59], v[52:53] op_sel:[0,0,1] op_sel_hi:[1,1,0] neg_lo:[0,0,1] neg_hi:[0,0,1]
	v_pk_fma_f32 v[48:49], v[44:45], v[48:49], v[52:53] op_sel:[0,0,1] op_sel_hi:[0,1,0]
	v_mov_b32_e32 v55, v49
	v_pk_mul_f32 v[52:53], v[44:45], v[54:55] op_sel:[1,0]
	v_div_scale_f32 v43, s[30:31], v33, v33, v51
	v_pk_fma_f32 v[56:57], v[44:45], v[54:55], v[52:53] op_sel:[0,0,1] op_sel_hi:[0,1,0] neg_lo:[0,0,1] neg_hi:[0,0,1]
	v_pk_fma_f32 v[52:53], v[44:45], v[54:55], v[52:53] op_sel:[0,0,1] op_sel_hi:[0,1,0]
	v_mov_b32_e32 v52, v56
	v_mov_b32_e32 v48, v56
	v_mov_b32_e32 v49, v53
	ds_write2_b64 v40, v[54:55], v[48:49] offset0:2 offset1:3
	v_pk_mul_f32 v[48:49], v[44:45], v[52:53] op_sel:[1,0]
	v_rcp_f32_e32 v47, v43
	v_pk_fma_f32 v[54:55], v[44:45], v[56:57], v[48:49] op_sel:[0,0,1] op_sel_hi:[1,1,0] neg_lo:[0,0,1] neg_hi:[0,0,1]
	v_pk_fma_f32 v[48:49], v[44:45], v[52:53], v[48:49] op_sel:[0,0,1] op_sel_hi:[0,1,0]
	v_mov_b32_e32 v55, v49
	v_pk_mul_f32 v[52:53], v[44:45], v[54:55] op_sel:[1,0]
	v_fma_f32 v50, -v43, v47, 1.0
	v_pk_fma_f32 v[56:57], v[44:45], v[54:55], v[52:53] op_sel:[0,0,1] op_sel_hi:[0,1,0] neg_lo:[0,0,1] neg_hi:[0,0,1]
	v_pk_fma_f32 v[52:53], v[44:45], v[54:55], v[52:53] op_sel:[0,0,1] op_sel_hi:[0,1,0]
	v_mov_b32_e32 v52, v56
	v_mov_b32_e32 v48, v56
	v_mov_b32_e32 v49, v53
	ds_write2_b64 v40, v[54:55], v[48:49] offset0:4 offset1:5
	v_pk_mul_f32 v[48:49], v[44:45], v[52:53] op_sel:[1,0]
	v_fmac_f32_e32 v47, v50, v47
	v_pk_fma_f32 v[54:55], v[44:45], v[56:57], v[48:49] op_sel:[0,0,1] op_sel_hi:[1,1,0] neg_lo:[0,0,1] neg_hi:[0,0,1]
	v_pk_fma_f32 v[48:49], v[44:45], v[52:53], v[48:49] op_sel:[0,0,1] op_sel_hi:[0,1,0]
	v_mov_b32_e32 v55, v49
	v_pk_mul_f32 v[52:53], v[44:45], v[54:55] op_sel:[1,0]
	s_nop 0
	v_pk_fma_f32 v[56:57], v[44:45], v[54:55], v[52:53] op_sel:[0,0,1] op_sel_hi:[0,1,0] neg_lo:[0,0,1] neg_hi:[0,0,1]
	v_pk_fma_f32 v[52:53], v[44:45], v[54:55], v[52:53] op_sel:[0,0,1] op_sel_hi:[0,1,0]
	v_mov_b32_e32 v52, v56
	v_mov_b32_e32 v48, v56
	v_mov_b32_e32 v49, v53
	ds_write2_b64 v40, v[54:55], v[48:49] offset0:6 offset1:7
	v_pk_mul_f32 v[48:49], v[44:45], v[52:53] op_sel:[1,0]
	s_nop 0
	v_pk_fma_f32 v[54:55], v[44:45], v[56:57], v[48:49] op_sel:[0,0,1] op_sel_hi:[1,1,0] neg_lo:[0,0,1] neg_hi:[0,0,1]
	v_pk_fma_f32 v[48:49], v[44:45], v[52:53], v[48:49] op_sel:[0,0,1] op_sel_hi:[0,1,0]
	v_mov_b32_e32 v55, v49
	v_pk_mul_f32 v[52:53], v[44:45], v[54:55] op_sel:[1,0]
	s_nop 0
	v_pk_fma_f32 v[56:57], v[44:45], v[54:55], v[52:53] op_sel:[0,0,1] op_sel_hi:[0,1,0] neg_lo:[0,0,1] neg_hi:[0,0,1]
	v_pk_fma_f32 v[52:53], v[44:45], v[54:55], v[52:53] op_sel:[0,0,1] op_sel_hi:[0,1,0]
	v_mov_b32_e32 v52, v56
	v_mov_b32_e32 v48, v56
	v_mov_b32_e32 v49, v53
	ds_write2_b64 v40, v[54:55], v[48:49] offset0:8 offset1:9
	v_pk_mul_f32 v[48:49], v[44:45], v[52:53] op_sel:[1,0]
	s_nop 0
	v_pk_fma_f32 v[54:55], v[44:45], v[56:57], v[48:49] op_sel:[0,0,1] op_sel_hi:[1,1,0] neg_lo:[0,0,1] neg_hi:[0,0,1]
	v_pk_fma_f32 v[48:49], v[44:45], v[52:53], v[48:49] op_sel:[0,0,1] op_sel_hi:[0,1,0]
	v_mov_b32_e32 v55, v49
	v_pk_mul_f32 v[52:53], v[44:45], v[54:55] op_sel:[1,0]
	s_nop 0
	v_pk_fma_f32 v[56:57], v[44:45], v[54:55], v[52:53] op_sel:[0,0,1] op_sel_hi:[0,1,0] neg_lo:[0,0,1] neg_hi:[0,0,1]
; __device__ __forceinline__ void s5_gen(LAS unsigned char* lds, const S5In P, int g, int q, bf16_t* Bst, bf16_t* Bout, const int tid) {
;     ...
;         const float nr = ar - 1.0f, ni = ai, den = lr * lr + li * li;
;         const float fr = (nr * lr + ni * li) / den, fi = (ni * lr - nr * li) / den;
;         float wr = 1.0f, wi = 0.0f;
;         for (int k = 0; k <= 16; ++k) { pw[(di * 64 + p) * 17 + k] = (f32x2v){wr, wi}; const float t = wr * ar - wi * ai; wi = wr * ai + wi * ar; wr = t; }
	v_pk_fma_f32 v[52:53], v[44:45], v[54:55], v[52:53] op_sel:[0,0,1] op_sel_hi:[0,1,0]
	v_mov_b32_e32 v52, v56
	v_mov_b32_e32 v48, v56
	v_mov_b32_e32 v49, v53
	ds_write2_b64 v40, v[54:55], v[48:49] offset0:10 offset1:11
	v_pk_mul_f32 v[48:49], v[44:45], v[52:53] op_sel:[1,0]
	s_nop 0
	v_pk_fma_f32 v[54:55], v[44:45], v[56:57], v[48:49] op_sel:[0,0,1] op_sel_hi:[1,1,0] neg_lo:[0,0,1] neg_hi:[0,0,1]
	v_pk_fma_f32 v[48:49], v[44:45], v[52:53], v[48:49] op_sel:[0,0,1] op_sel_hi:[0,1,0]
	v_mov_b32_e32 v55, v49
	v_pk_mul_f32 v[52:53], v[44:45], v[54:55] op_sel:[1,0]
	s_nop 0
	v_pk_fma_f32 v[56:57], v[44:45], v[54:55], v[52:53] op_sel:[0,0,1] op_sel_hi:[0,1,0] neg_lo:[0,0,1] neg_hi:[0,0,1]
	v_pk_fma_f32 v[52:53], v[44:45], v[54:55], v[52:53] op_sel:[0,0,1] op_sel_hi:[0,1,0]
	v_mov_b32_e32 v52, v56
	v_mov_b32_e32 v48, v56
	v_mov_b32_e32 v49, v53
	ds_write2_b64 v40, v[54:55], v[48:49] offset0:12 offset1:13
	v_pk_mul_f32 v[48:49], v[44:45], v[52:53] op_sel:[1,0]
	s_nop 0
	v_pk_fma_f32 v[54:55], v[44:45], v[56:57], v[48:49] op_sel:[0,0,1] op_sel_hi:[1,1,0] neg_lo:[0,0,1] neg_hi:[0,0,1]
	v_pk_fma_f32 v[48:49], v[44:45], v[52:53], v[48:49] op_sel:[0,0,1] op_sel_hi:[0,1,0]
	v_mov_b32_e32 v55, v49
	v_pk_mul_f32 v[52:53], v[44:45], v[54:55] op_sel:[1,0]
	s_nop 0
	v_pk_fma_f32 v[56:57], v[44:45], v[54:55], v[52:53] op_sel:[0,0,1] op_sel_hi:[0,1,0] neg_lo:[0,0,1] neg_hi:[0,0,1]
	v_pk_fma_f32 v[52:53], v[44:45], v[54:55], v[52:53] op_sel:[0,0,1] op_sel_hi:[0,1,0]
	v_mov_b32_e32 v52, v56
	v_mov_b32_e32 v48, v56
	v_mov_b32_e32 v49, v53
	ds_write2_b64 v40, v[54:55], v[48:49] offset0:14 offset1:15
	v_pk_mul_f32 v[48:49], v[44:45], v[52:53] op_sel:[1,0]
	s_nop 0
	v_pk_fma_f32 v[54:55], v[44:45], v[56:57], v[48:49] op_sel:[0,0,1] op_sel_hi:[1,1,0] neg_lo:[0,0,1] neg_hi:[0,0,1]
	v_pk_fma_f32 v[44:45], v[44:45], v[52:53], v[48:49] op_sel:[0,0,1] op_sel_hi:[0,1,0]
	v_div_scale_f32 v44, vcc, v51, v33, v51
	v_mov_b32_e32 v55, v45
	v_mul_f32_e32 v45, v44, v47
	v_fma_f32 v48, -v43, v45, v44
	v_fmac_f32_e32 v45, v48, v47
	v_fma_f32 v43, -v43, v45, v44
	v_div_scale_f32 v44, s[30:31], v32, v32, v46
	v_rcp_f32_e32 v48, v44
	v_div_fmas_f32 v43, v43, v47, v45
	v_div_fixup_f32 v33, v43, v33, v51
	ds_write_b64 v40, v[54:55] offset:128
	v_fma_f32 v43, -v44, v48, 1.0
	v_fmac_f32_e32 v48, v43, v48
	v_div_scale_f32 v43, vcc, v46, v32, v46
	v_mul_f32_e32 v45, v43, v48
	v_fma_f32 v47, -v44, v45, v43
	v_fmac_f32_e32 v45, v47, v48
	v_fma_f32 v43, -v44, v45, v43
	v_div_fmas_f32 v43, v43, v48, v45
	v_div_fixup_f32 v32, v43, v32, v46
	s_waitcnt vmcnt(0)
; __device__ __forceinline__ void s5_gen(LAS unsigned char* lds, const S5In P, int g, int q, bf16_t* Bst, bf16_t* Bout, const int tid) {
;     ...
;         for (int c = 0; c < 16; ++c) { const float br = P.b_re[(size_t)gp * 16 + c], bi = P.b_im[(size_t)gp * 16 + c];
;             bb[(di * 64 + p) * 16 + c] = (f32x2v){fr * br - fi * bi, fr * bi + fi * br}; }
;     }
;     for (int e = tid; e < 2048; e += 512) { const int di = e >> 10, c = (e >> 6) & 15, p = e & 63; const size_t o = ((size_t)(di * 64 + g) * 16 + c) * 64 + p; cc[e] = (f32x2v){P.c_re[o], P.c_im[o]}; }
	v_pk_mul_f32 v[46:47], v[32:33], v[28:29] op_sel:[1,0] op_sel_hi:[0,0]
	v_pk_fma_f32 v[44:45], v[32:33], v[16:17], v[46:47] neg_lo:[0,0,1] neg_hi:[0,0,1]
	v_pk_fma_f32 v[48:49], v[32:33], v[16:17], v[46:47] op_sel_hi:[1,0,1]
	v_pk_mul_f32 v[28:29], v[32:33], v[28:29] op_sel:[1,1] op_sel_hi:[0,1]
	v_mov_b32_e32 v46, v17
	v_pk_fma_f32 v[46:47], v[32:33], v[46:47], v[28:29] neg_lo:[0,0,1] neg_hi:[0,0,1]
	v_pk_fma_f32 v[16:17], v[32:33], v[16:17], v[28:29] op_sel:[0,1,0]
	v_pk_mul_f32 v[28:29], v[32:33], v[30:31] op_sel:[1,0] op_sel_hi:[0,0]
	v_mov_b32_e32 v47, v17
	v_pk_fma_f32 v[16:17], v[32:33], v[18:19], v[28:29] neg_lo:[0,0,1] neg_hi:[0,0,1]
	v_pk_fma_f32 v[28:29], v[32:33], v[18:19], v[28:29] op_sel_hi:[1,0,1]
	v_mov_b32_e32 v18, v31
	v_pk_mul_f32 v[30:31], v[32:33], v[18:19] op_sel:[1,0] op_sel_hi:[0,0]
	v_mov_b32_e32 v18, v19
	v_mov_b32_e32 v28, v19
	v_pk_fma_f32 v[18:19], v[32:33], v[18:19], v[30:31] neg_lo:[0,0,1] neg_hi:[0,0,1]
	v_pk_fma_f32 v[30:31], v[32:33], v[28:29], v[30:31] op_sel_hi:[1,0,1]
	v_mov_b32_e32 v17, v29
	v_mov_b32_e32 v19, v31
	ds_write_b128 v41, v[16:19] offset:17424
	v_pk_mul_f32 v[18:19], v[32:33], v[24:25] op_sel:[1,0] op_sel_hi:[0,0]
	v_pk_fma_f32 v[16:17], v[32:33], v[12:13], v[18:19] neg_lo:[0,0,1] neg_hi:[0,0,1]
	v_pk_fma_f32 v[28:29], v[32:33], v[12:13], v[18:19] op_sel_hi:[1,0,1]
	v_pk_mul_f32 v[24:25], v[32:33], v[24:25] op_sel:[1,1] op_sel_hi:[0,1]
	v_mov_b32_e32 v18, v13
	v_pk_fma_f32 v[18:19], v[32:33], v[18:19], v[24:25] neg_lo:[0,0,1] neg_hi:[0,0,1]
	v_pk_fma_f32 v[12:13], v[32:33], v[12:13], v[24:25] op_sel:[0,1,0]
	v_mov_b32_e32 v17, v29
	v_mov_b32_e32 v19, v13
	ds_write_b128 v41, v[16:19] offset:17440
	v_pk_mul_f32 v[16:17], v[32:33], v[26:27] op_sel:[1,0] op_sel_hi:[0,0]
	v_pk_fma_f32 v[12:13], v[32:33], v[14:15], v[16:17] neg_lo:[0,0,1] neg_hi:[0,0,1]
	v_pk_fma_f32 v[16:17], v[32:33], v[14:15], v[16:17] op_sel_hi:[1,0,1]
	v_mov_b32_e32 v14, v27
	v_pk_mul_f32 v[18:19], v[32:33], v[14:15] op_sel:[1,0] op_sel_hi:[0,0]
	v_mov_b32_e32 v14, v15
	v_mov_b32_e32 v16, v15
	v_pk_fma_f32 v[14:15], v[32:33], v[14:15], v[18:19] neg_lo:[0,0,1] neg_hi:[0,0,1]
	v_pk_fma_f32 v[18:19], v[32:33], v[16:17], v[18:19] op_sel_hi:[1,0,1]
	v_mov_b32_e32 v13, v17
	v_mov_b32_e32 v15, v19
	ds_write_b128 v41, v[12:15] offset:17456
	v_pk_mul_f32 v[14:15], v[32:33], v[20:21] op_sel:[1,0] op_sel_hi:[0,0]
	v_pk_fma_f32 v[12:13], v[32:33], v[8:9], v[14:15] neg_lo:[0,0,1] neg_hi:[0,0,1]
	v_pk_fma_f32 v[16:17], v[32:33], v[8:9], v[14:15] op_sel_hi:[1,0,1]
	v_pk_mul_f32 v[18:19], v[32:33], v[20:21] op_sel:[1,1] op_sel_hi:[0,1]
	v_mov_b32_e32 v14, v9
	v_pk_fma_f32 v[14:15], v[32:33], v[14:15], v[18:19] neg_lo:[0,0,1] neg_hi:[0,0,1]
	v_pk_fma_f32 v[8:9], v[32:33], v[8:9], v[18:19] op_sel:[0,1,0]
	v_mov_b32_e32 v13, v17
	v_mov_b32_e32 v15, v9
	ds_write_b128 v41, v[12:15] offset:17472
	v_pk_mul_f32 v[12:13], v[32:33], v[22:23] op_sel:[1,0] op_sel_hi:[0,0]
	v_pk_fma_f32 v[8:9], v[32:33], v[10:11], v[12:13] neg_lo:[0,0,1] neg_hi:[0,0,1]
	v_pk_fma_f32 v[12:13], v[32:33], v[10:11], v[12:13] op_sel_hi:[1,0,1]
	v_mov_b32_e32 v10, v23
	v_pk_mul_f32 v[14:15], v[32:33], v[10:11] op_sel:[1,0] op_sel_hi:[0,0]
	v_mov_b32_e32 v10, v11
	v_mov_b32_e32 v12, v11
	v_pk_fma_f32 v[10:11], v[32:33], v[10:11], v[14:15] neg_lo:[0,0,1] neg_hi:[0,0,1]
	v_pk_fma_f32 v[14:15], v[32:33], v[12:13], v[14:15] op_sel_hi:[1,0,1]
	v_mov_b32_e32 v9, v13
	v_mov_b32_e32 v11, v15
	ds_write_b128 v41, v[8:11] offset:17488
	v_pk_mul_f32 v[10:11], v[32:33], v[4:5] op_sel:[1,0] op_sel_hi:[0,0]
	v_pk_fma_f32 v[8:9], v[32:33], v[0:1], v[10:11] neg_lo:[0,0,1] neg_hi:[0,0,1]
	v_pk_fma_f32 v[12:13], v[32:33], v[0:1], v[10:11] op_sel_hi:[1,0,1]
	v_pk_mul_f32 v[4:5], v[32:33], v[4:5] op_sel:[1,1] op_sel_hi:[0,1]
	v_mov_b32_e32 v10, v1
	v_pk_fma_f32 v[10:11], v[32:33], v[10:11], v[4:5] neg_lo:[0,0,1] neg_hi:[0,0,1]
	v_pk_fma_f32 v[0:1], v[32:33], v[0:1], v[4:5] op_sel:[0,1,0]
	v_pk_mul_f32 v[4:5], v[32:33], v[6:7] op_sel:[1,0] op_sel_hi:[0,0]
	v_mov_b32_e32 v11, v1
	v_pk_fma_f32 v[0:1], v[32:33], v[2:3], v[4:5] neg_lo:[0,0,1] neg_hi:[0,0,1]
	v_pk_fma_f32 v[4:5], v[32:33], v[2:3], v[4:5] op_sel_hi:[1,0,1]
	v_mov_b32_e32 v2, v7
	v_pk_mul_f32 v[6:7], v[32:33], v[2:3] op_sel:[1,0] op_sel_hi:[0,0]
	v_mov_b32_e32 v2, v3
	v_mov_b32_e32 v4, v3
	v_pk_fma_f32 v[2:3], v[32:33], v[2:3], v[6:7] neg_lo:[0,0,1] neg_hi:[0,0,1]
	v_pk_fma_f32 v[6:7], v[32:33], v[4:5], v[6:7] op_sel_hi:[1,0,1]
	v_mov_b32_e32 v45, v49
	v_mov_b32_e32 v9, v13
	v_mov_b32_e32 v1, v5
	v_mov_b32_e32 v3, v7
	ds_write_b128 v41, v[44:47] offset:17408
	ds_write_b128 v41, v[8:11] offset:17504
	ds_write_b128 v41, v[0:3] offset:17520
.LBB0_194:
	s_or_b64 exec, exec, s[28:29]
	s_and_saveexec_b64 s[28:29], s[38:39]
	s_movk_i32 s42, 0x5ff
	s_cbranch_execz .LBB0_197
	s_movk_i32 s17, 0xff
	v_cmp_lt_u32_e32 vcc, s17, v66
	s_and_b64 exec, exec, vcc
	s_cbranch_execz .LBB0_197
	s_lshl_b32 s17, s16, 10
	s_sub_i32 s17, s17, 0x100
	v_add_u32_e32 v0, s17, v66
	v_lshlrev_b32_e32 v208, 2, v0
	v_lshl_add_u64 v[0:1], s[82:83], 0, v[208:209]
	v_lshl_add_u64 v[2:3], s[90:91], 0, v[208:209]
	s_mov_b64 s[30:31], 0x40000
	v_lshl_add_u64 v[4:5], v[0:1], 0, s[30:31]
	v_lshl_add_u64 v[22:23], v[2:3], 0, s[30:31]
	global_load_dword v6, v[0:1], off
	global_load_dword v7, v[2:3], off
	global_load_dword v8, v[0:1], off offset:1024
	global_load_dword v9, v[2:3], off offset:1024
	global_load_dword v10, v[0:1], off offset:2048
	global_load_dword v11, v[2:3], off offset:2048
	global_load_dword v12, v[0:1], off offset:3072
	global_load_dword v13, v[2:3], off offset:3072
	global_load_dword v14, v[4:5], off
	global_load_dword v15, v[22:23], off
	global_load_dword v16, v[4:5], off offset:1024
	global_load_dword v17, v[22:23], off offset:1024
	global_load_dword v18, v[4:5], off offset:2048
	global_load_dword v19, v[22:23], off offset:2048
	global_load_dword v20, v[4:5], off offset:3072
	global_load_dword v21, v[22:23], off offset:3072
	v_add_u32_e32 v24, 0xfffff800, v35
	s_waitcnt vmcnt(0)
	ds_write_b64 v24, v[6:7]
	ds_write_b64 v24, v[8:9] offset:2048
	ds_write_b64 v24, v[10:11] offset:4096
	ds_write_b64 v24, v[12:13] offset:6144
	ds_write_b64 v24, v[14:15] offset:8192
	ds_write_b64 v24, v[16:17] offset:10240
	ds_write_b64 v24, v[18:19] offset:12288
	ds_write_b64 v24, v[20:21] offset:14336

; __device__ __forceinline__ void s5_gen(LAS unsigned char* lds, const S5In P, int g, int q, bf16_t* Bst, bf16_t* Bout, const int tid) {
;     ...
;       for (int p = 0; p < 64; ++p) { const f32x2v w = pw[(di * 64 + p) * 17 + k]; float zr[4], zi[4];
; #pragma unroll
;           for (int b_ = 0; b_ < 4; ++b_) { const f32x2v b = bb[(di * 64 + p) * 16 + 4 * c2b + b_]; zr[b_] = w.x * b.x - w.y * b.y; zi[b_] = w.x * b.y + w.y * b.x; }
; #pragma unroll
;           for (int a_ = 0; a_ < 4; ++a_) { const f32x2v C = cc[(di * 16 + 4 * chb + a_) * 64 + p];
; #pragma unroll
;               for (int b_ = 0; b_ < 4; ++b_) acc[a_][b_] += C.x * zr[b_] - C.y * zi[b_]; } }
.LBB0_198:
	ds_read2_b64 v[20:23], v43 offset1:17
	ds_read_b128 v[28:31], v44
	ds_read_b128 v[46:49], v44 offset:16
	v_add_u32_e32 v45, s17, v36
	ds_read_b128 v[24:27], v45
	ds_read_b128 v[16:19], v45 offset:16
	s_add_i32 s17, s17, 32
	s_waitcnt lgkmcnt(0)
	v_mov_b32_e32 v50, v29
	v_mov_b32_e32 v51, v31
	v_mov_b32_e32 v32, v28
	v_mov_b32_e32 v33, v30
	v_pk_mul_f32 v[50:51], v[20:21], v[50:51] op_sel:[1,0]
	s_cmpk_eq_i32 s17, 0x200
	v_pk_fma_f32 v[32:33], v[20:21], v[32:33], v[50:51] op_sel_hi:[0,1,1] neg_lo:[0,0,1] neg_hi:[0,0,1]
	v_mov_b32_e32 v50, v28
	v_pk_mov_b32 v[28:29], v[28:29], v[30:31] op_sel:[1,0]
	v_mov_b32_e32 v51, v31
	v_pk_mul_f32 v[28:29], v[20:21], v[28:29]
	s_waitcnt lgkmcnt(2)
	v_mov_b32_e32 v30, v47
	v_pk_fma_f32 v[50:51], v[20:21], v[50:51], v[28:29] op_sel:[1,0,0] op_sel_hi:[0,1,1]
	s_waitcnt lgkmcnt(1)
	v_pk_mul_f32 v[28:29], v[50:51], v[24:25] op_sel:[0,1]
	v_mov_b32_e32 v31, v49
	v_pk_fma_f32 v[28:29], v[32:33], v[24:25], v[28:29] op_sel_hi:[1,0,1] neg_lo:[0,0,1] neg_hi:[0,0,1]
	v_pk_mul_f32 v[30:31], v[20:21], v[30:31] op_sel:[1,0]
	v_pk_add_f32 v[28:29], v[0:1], v[28:29]
	v_mov_b32_e32 v0, v46
	v_mov_b32_e32 v1, v48
	v_pk_fma_f32 v[52:53], v[20:21], v[0:1], v[30:31] op_sel_hi:[0,1,1] neg_lo:[0,0,1] neg_hi:[0,0,1]
	v_pk_mov_b32 v[30:31], v[46:47], v[48:49] op_sel:[1,0]
	v_mov_b32_e32 v1, v49
	v_pk_mul_f32 v[30:31], v[20:21], v[30:31]
	s_nop 0
	v_pk_fma_f32 v[46:47], v[20:21], v[0:1], v[30:31] op_sel:[1,0,0] op_sel_hi:[0,1,1]
	v_pk_mul_f32 v[0:1], v[24:25], v[46:47] op_sel:[1,0]
	s_nop 0
	v_pk_fma_f32 v[0:1], v[24:25], v[52:53], v[0:1] op_sel_hi:[0,1,1] neg_lo:[0,0,1] neg_hi:[0,0,1]
	v_pk_add_f32 v[20:21], v[2:3], v[0:1]
	ds_read_b128 v[0:3], v45 offset:512
	s_waitcnt lgkmcnt(0)
	v_pk_mul_f32 v[24:25], v[50:51], v[0:1] op_sel:[0,1]
	s_nop 0
	v_pk_fma_f32 v[24:25], v[32:33], v[0:1], v[24:25] op_sel_hi:[1,0,1] neg_lo:[0,0,1] neg_hi:[0,0,1]
	s_nop 0
	v_pk_add_f32 v[24:25], v[12:13], v[24:25]
	v_pk_mul_f32 v[12:13], v[0:1], v[46:47] op_sel:[1,0]
	s_nop 0
	v_pk_fma_f32 v[0:1], v[0:1], v[52:53], v[12:13] op_sel_hi:[0,1,1] neg_lo:[0,0,1] neg_hi:[0,0,1]
	v_pk_add_f32 v[0:1], v[14:15], v[0:1]
	ds_read_b128 v[12:15], v45 offset:1024
	s_waitcnt lgkmcnt(0)
	v_pk_mul_f32 v[30:31], v[50:51], v[12:13] op_sel:[0,1]
	s_nop 0
	v_pk_fma_f32 v[30:31], v[32:33], v[12:13], v[30:31] op_sel_hi:[1,0,1] neg_lo:[0,0,1] neg_hi:[0,0,1]
	s_nop 0
	v_pk_add_f32 v[30:31], v[8:9], v[30:31]
	v_pk_mul_f32 v[8:9], v[46:47], v[12:13] op_sel:[0,1]
	s_nop 0
	v_pk_fma_f32 v[8:9], v[52:53], v[12:13], v[8:9] op_sel_hi:[1,0,1] neg_lo:[0,0,1] neg_hi:[0,0,1]
	s_nop 0
	v_pk_add_f32 v[12:13], v[10:11], v[8:9]
	ds_read_b128 v[8:11], v45 offset:1536
	s_waitcnt lgkmcnt(0)
	v_pk_mul_f32 v[48:49], v[50:51], v[8:9] op_sel:[0,1]
	s_nop 0
	v_pk_fma_f32 v[32:33], v[32:33], v[8:9], v[48:49] op_sel_hi:[1,0,1] neg_lo:[0,0,1] neg_hi:[0,0,1]
	s_nop 0
	v_pk_add_f32 v[4:5], v[4:5], v[32:33]
	v_pk_mul_f32 v[32:33], v[46:47], v[8:9] op_sel:[0,1]
	s_nop 0
	v_pk_fma_f32 v[8:9], v[52:53], v[8:9], v[32:33] op_sel_hi:[1,0,1] neg_lo:[0,0,1] neg_hi:[0,0,1]
	ds_read_b128 v[46:49], v44 offset:128
	ds_read_b128 v[50:53], v44 offset:144
	v_pk_add_f32 v[6:7], v[6:7], v[8:9]
	s_waitcnt lgkmcnt(0)
	v_mov_b32_e32 v32, v47
	v_mov_b32_e32 v33, v49
	v_mov_b32_e32 v8, v46
	v_mov_b32_e32 v9, v48
	v_pk_mul_f32 v[32:33], v[22:23], v[32:33] op_sel:[1,0]
	v_pk_mov_b32 v[46:47], v[46:47], v[48:49] op_sel:[1,0]
	v_pk_fma_f32 v[32:33], v[22:23], v[8:9], v[32:33] op_sel_hi:[0,1,1] neg_lo:[0,0,1] neg_hi:[0,0,1]
	v_mov_b32_e32 v9, v49
	v_pk_mul_f32 v[46:47], v[22:23], v[46:47]
	v_mov_b32_e32 v48, v27
	v_pk_fma_f32 v[46:47], v[22:23], v[8:9], v[46:47] op_sel:[1,0,0] op_sel_hi:[0,1,1]
	v_pk_mul_f32 v[8:9], v[46:47], v[48:49] op_sel_hi:[1,0]
	s_waitcnt lgkmcnt(0)
	v_mov_b32_e32 v54, v51
	v_pk_fma_f32 v[8:9], v[32:33], v[26:27], v[8:9] op_sel_hi:[1,0,1] neg_lo:[0,0,1] neg_hi:[0,0,1]
	v_mov_b32_e32 v55, v53
	v_pk_add_f32 v[8:9], v[28:29], v[8:9]
	v_mov_b32_e32 v28, v50
	v_mov_b32_e32 v29, v52
	v_pk_mul_f32 v[54:55], v[22:23], v[54:55] op_sel:[1,0]
	v_pk_mov_b32 v[50:51], v[50:51], v[52:53] op_sel:[1,0]
	v_pk_fma_f32 v[54:55], v[22:23], v[28:29], v[54:55] op_sel_hi:[0,1,1] neg_lo:[0,0,1] neg_hi:[0,0,1]
	v_mov_b32_e32 v29, v53
	v_pk_mul_f32 v[50:51], v[22:23], v[50:51]
	s_nop 0
	v_pk_fma_f32 v[50:51], v[22:23], v[28:29], v[50:51] op_sel:[1,0,0] op_sel_hi:[0,1,1]
	v_pk_mul_f32 v[22:23], v[48:49], v[50:51] op_sel_hi:[0,1]
	v_pk_fma_f32 v[22:23], v[26:27], v[54:55], v[22:23] op_sel_hi:[0,1,1] neg_lo:[0,0,1] neg_hi:[0,0,1]
	v_mov_b32_e32 v26, v3
	v_pk_add_f32 v[20:21], v[20:21], v[22:23]
	v_pk_mul_f32 v[22:23], v[46:47], v[26:27] op_sel_hi:[1,0]
	s_nop 0
	v_pk_fma_f32 v[22:23], v[32:33], v[2:3], v[22:23] op_sel_hi:[1,0,1] neg_lo:[0,0,1] neg_hi:[0,0,1]
	s_nop 0
	v_pk_add_f32 v[22:23], v[24:25], v[22:23]
	v_pk_mul_f32 v[24:25], v[26:27], v[50:51] op_sel_hi:[0,1]
	v_pk_fma_f32 v[2:3], v[2:3], v[54:55], v[24:25] op_sel_hi:[0,1,1] neg_lo:[0,0,1] neg_hi:[0,0,1]
	v_pk_add_f32 v[24:25], v[0:1], v[2:3]
	v_mov_b32_e32 v0, v15
	v_pk_mul_f32 v[2:3], v[46:47], v[0:1] op_sel_hi:[1,0]
	v_pk_mul_f32 v[0:1], v[50:51], v[0:1] op_sel_hi:[1,0]
	v_pk_fma_f32 v[2:3], v[32:33], v[14:15], v[2:3] op_sel_hi:[1,0,1] neg_lo:[0,0,1] neg_hi:[0,0,1]
	v_pk_fma_f32 v[0:1], v[54:55], v[14:15], v[0:1] op_sel_hi:[1,0,1] neg_lo:[0,0,1] neg_hi:[0,0,1]
	v_pk_add_f32 v[26:27], v[30:31], v[2:3]
	v_pk_add_f32 v[12:13], v[12:13], v[0:1]
	v_mov_b32_e32 v0, v11
	v_pk_mul_f32 v[2:3], v[46:47], v[0:1] op_sel_hi:[1,0]
	v_pk_mul_f32 v[0:1], v[50:51], v[0:1] op_sel_hi:[1,0]
	v_pk_fma_f32 v[2:3], v[32:33], v[10:11], v[2:3] op_sel_hi:[1,0,1] neg_lo:[0,0,1] neg_hi:[0,0,1]
	v_pk_fma_f32 v[0:1], v[54:55], v[10:11], v[0:1] op_sel_hi:[1,0,1] neg_lo:[0,0,1] neg_hi:[0,0,1]
	v_pk_add_f32 v[28:29], v[4:5], v[2:3]
	v_pk_add_f32 v[30:31], v[6:7], v[0:1]
	ds_read2_b64 v[0:3], v43 offset0:34 offset1:51
	ds_read_b128 v[4:7], v44 offset:256
	ds_read_b128 v[46:49], v44 offset:272
	v_add_u32_e32 v43, 0x220, v43
	s_waitcnt lgkmcnt(0)
; __device__ __forceinline__ void s5_gen(LAS unsigned char* lds, const S5In P, int g, int q, bf16_t* Bst, bf16_t* Bout, const int tid) {
;     ...
;       for (int p = 0; p < 64; ++p) { const f32x2v w = pw[(di * 64 + p) * 17 + k]; float zr[4], zi[4];
; #pragma unroll
;           for (int b_ = 0; b_ < 4; ++b_) { const f32x2v b = bb[(di * 64 + p) * 16 + 4 * c2b + b_]; zr[b_] = w.x * b.x - w.y * b.y; zi[b_] = w.x * b.y + w.y * b.x; }
; #pragma unroll
;           for (int a_ = 0; a_ < 4; ++a_) { const f32x2v C = cc[(di * 16 + 4 * chb + a_) * 64 + p];
; #pragma unroll
;               for (int b_ = 0; b_ < 4; ++b_) acc[a_][b_] += C.x * zr[b_] - C.y * zi[b_]; } }
; #pragma unroll
;       for (int a_ = 0; a_ < 4; ++a_)
; #pragma unroll
;           for (int b_ = 0; b_ < 4; ++b_) kt[((di * 16 + k) * 16 + 4 * chb + a_) * 16 + 4 * c2b + b_] = acc[a_][b_]; }
	v_mov_b32_e32 v14, v5
	v_mov_b32_e32 v15, v7
	v_mov_b32_e32 v10, v4
	v_mov_b32_e32 v11, v6
	v_pk_mul_f32 v[14:15], v[0:1], v[14:15] op_sel:[1,0]
	v_pk_mov_b32 v[4:5], v[4:5], v[6:7] op_sel:[1,0]
	v_pk_fma_f32 v[50:51], v[0:1], v[10:11], v[14:15] op_sel_hi:[0,1,1] neg_lo:[0,0,1] neg_hi:[0,0,1]
	v_mov_b32_e32 v11, v7
	v_pk_mul_f32 v[4:5], v[0:1], v[4:5]
	s_waitcnt lgkmcnt(0)
	v_mov_b32_e32 v6, v47
	v_pk_fma_f32 v[52:53], v[0:1], v[10:11], v[4:5] op_sel:[1,0,0] op_sel_hi:[0,1,1]
	v_pk_mul_f32 v[4:5], v[52:53], v[16:17] op_sel:[0,1]
	v_mov_b32_e32 v7, v49
	v_pk_fma_f32 v[4:5], v[50:51], v[16:17], v[4:5] op_sel_hi:[1,0,1] neg_lo:[0,0,1] neg_hi:[0,0,1]
	v_pk_mul_f32 v[6:7], v[0:1], v[6:7] op_sel:[1,0]
	v_pk_add_f32 v[32:33], v[8:9], v[4:5]
	v_mov_b32_e32 v4, v46
	v_mov_b32_e32 v5, v48
	v_pk_fma_f32 v[54:55], v[0:1], v[4:5], v[6:7] op_sel_hi:[0,1,1] neg_lo:[0,0,1] neg_hi:[0,0,1]
	v_pk_mov_b32 v[6:7], v[46:47], v[48:49] op_sel:[1,0]
	v_mov_b32_e32 v5, v49
	v_pk_mul_f32 v[6:7], v[0:1], v[6:7]
	s_nop 0
	v_pk_fma_f32 v[0:1], v[0:1], v[4:5], v[6:7] op_sel:[1,0,0] op_sel_hi:[0,1,1]
	v_pk_mul_f32 v[4:5], v[16:17], v[0:1] op_sel:[1,0]
	s_nop 0
	v_pk_fma_f32 v[4:5], v[16:17], v[54:55], v[4:5] op_sel_hi:[0,1,1] neg_lo:[0,0,1] neg_hi:[0,0,1]
	v_pk_add_f32 v[20:21], v[20:21], v[4:5]
	ds_read_b128 v[4:7], v45 offset:528
	s_waitcnt lgkmcnt(0)
	v_pk_mul_f32 v[8:9], v[52:53], v[4:5] op_sel:[0,1]
	s_nop 0
	v_pk_fma_f32 v[8:9], v[50:51], v[4:5], v[8:9] op_sel_hi:[1,0,1] neg_lo:[0,0,1] neg_hi:[0,0,1]
	s_nop 0
	v_pk_add_f32 v[22:23], v[22:23], v[8:9]
	v_pk_mul_f32 v[8:9], v[4:5], v[0:1] op_sel:[1,0]
	s_nop 0
	v_pk_fma_f32 v[4:5], v[4:5], v[54:55], v[8:9] op_sel_hi:[0,1,1] neg_lo:[0,0,1] neg_hi:[0,0,1]
	ds_read_b128 v[8:11], v45 offset:1040
	v_pk_add_f32 v[4:5], v[24:25], v[4:5]
	s_waitcnt lgkmcnt(0)
	v_pk_mul_f32 v[14:15], v[52:53], v[8:9] op_sel:[0,1]
	s_nop 0
	v_pk_fma_f32 v[14:15], v[50:51], v[8:9], v[14:15] op_sel_hi:[1,0,1] neg_lo:[0,0,1] neg_hi:[0,0,1]
	s_nop 0
	v_pk_add_f32 v[24:25], v[26:27], v[14:15]
	v_pk_mul_f32 v[14:15], v[0:1], v[8:9] op_sel:[0,1]
	s_nop 0
	v_pk_fma_f32 v[8:9], v[54:55], v[8:9], v[14:15] op_sel_hi:[1,0,1] neg_lo:[0,0,1] neg_hi:[0,0,1]
	ds_read_b128 v[14:17], v45 offset:1552
	v_pk_add_f32 v[26:27], v[12:13], v[8:9]
	s_waitcnt lgkmcnt(0)
	v_pk_mul_f32 v[8:9], v[52:53], v[14:15] op_sel:[0,1]
	v_pk_mul_f32 v[0:1], v[0:1], v[14:15] op_sel:[0,1]
	v_pk_fma_f32 v[8:9], v[50:51], v[14:15], v[8:9] op_sel_hi:[1,0,1] neg_lo:[0,0,1] neg_hi:[0,0,1]
	v_pk_fma_f32 v[0:1], v[54:55], v[14:15], v[0:1] op_sel_hi:[1,0,1] neg_lo:[0,0,1] neg_hi:[0,0,1]
	ds_read_b128 v[12:15], v44 offset:384
	ds_read_b128 v[46:49], v44 offset:400
	v_pk_add_f32 v[28:29], v[28:29], v[8:9]
	v_pk_add_f32 v[30:31], v[30:31], v[0:1]
	v_add_u32_e32 v44, 0x200, v44
	s_waitcnt lgkmcnt(0)
	v_mov_b32_e32 v8, v13
	v_mov_b32_e32 v9, v15
	v_mov_b32_e32 v0, v12
	v_mov_b32_e32 v1, v14
	v_pk_mul_f32 v[8:9], v[2:3], v[8:9] op_sel:[1,0]
	s_nop 0
	v_pk_fma_f32 v[50:51], v[2:3], v[0:1], v[8:9] op_sel_hi:[0,1,1] neg_lo:[0,0,1] neg_hi:[0,0,1]
	v_pk_mov_b32 v[8:9], v[12:13], v[14:15] op_sel:[1,0]
	v_mov_b32_e32 v1, v15
	v_pk_mul_f32 v[8:9], v[2:3], v[8:9]
	s_waitcnt lgkmcnt(0)
	v_mov_b32_e32 v14, v47
	v_pk_fma_f32 v[52:53], v[2:3], v[0:1], v[8:9] op_sel:[1,0,0] op_sel_hi:[0,1,1]
	v_mov_b32_e32 v8, v19
	v_pk_mul_f32 v[0:1], v[52:53], v[8:9] op_sel_hi:[1,0]
	v_mov_b32_e32 v15, v49
	v_pk_fma_f32 v[0:1], v[50:51], v[18:19], v[0:1] op_sel_hi:[1,0,1] neg_lo:[0,0,1] neg_hi:[0,0,1]
	v_mov_b32_e32 v12, v46
	v_mov_b32_e32 v13, v48
	v_pk_mul_f32 v[14:15], v[2:3], v[14:15] op_sel:[1,0]
	v_pk_add_f32 v[0:1], v[32:33], v[0:1]
	v_pk_fma_f32 v[32:33], v[2:3], v[12:13], v[14:15] op_sel_hi:[0,1,1] neg_lo:[0,0,1] neg_hi:[0,0,1]
	v_pk_mov_b32 v[14:15], v[46:47], v[48:49] op_sel:[1,0]
	v_mov_b32_e32 v13, v49
	v_pk_mul_f32 v[14:15], v[2:3], v[14:15]
	s_nop 0
	v_pk_fma_f32 v[46:47], v[2:3], v[12:13], v[14:15] op_sel:[1,0,0] op_sel_hi:[0,1,1]
	v_pk_mul_f32 v[2:3], v[8:9], v[46:47] op_sel_hi:[0,1]
	v_mov_b32_e32 v8, v7
	v_pk_mul_f32 v[12:13], v[52:53], v[8:9] op_sel_hi:[1,0]
	v_pk_mul_f32 v[8:9], v[8:9], v[46:47] op_sel_hi:[0,1]
	v_pk_fma_f32 v[12:13], v[50:51], v[6:7], v[12:13] op_sel_hi:[1,0,1] neg_lo:[0,0,1] neg_hi:[0,0,1]
	v_pk_fma_f32 v[6:7], v[6:7], v[32:33], v[8:9] op_sel_hi:[0,1,1] neg_lo:[0,0,1] neg_hi:[0,0,1]
	v_pk_add_f32 v[14:15], v[4:5], v[6:7]
	v_mov_b32_e32 v4, v11
	v_pk_mul_f32 v[6:7], v[52:53], v[4:5] op_sel_hi:[1,0]
	v_pk_mul_f32 v[4:5], v[46:47], v[4:5] op_sel_hi:[1,0]
	v_pk_fma_f32 v[6:7], v[50:51], v[10:11], v[6:7] op_sel_hi:[1,0,1] neg_lo:[0,0,1] neg_hi:[0,0,1]
	v_pk_fma_f32 v[4:5], v[32:33], v[10:11], v[4:5] op_sel_hi:[1,0,1] neg_lo:[0,0,1] neg_hi:[0,0,1]
	v_pk_add_f32 v[8:9], v[24:25], v[6:7]
	v_mov_b32_e32 v6, v17
	v_pk_add_f32 v[10:11], v[26:27], v[4:5]
	v_pk_mul_f32 v[4:5], v[52:53], v[6:7] op_sel_hi:[1,0]
	v_pk_mul_f32 v[6:7], v[46:47], v[6:7] op_sel_hi:[1,0]
	v_pk_fma_f32 v[2:3], v[18:19], v[32:33], v[2:3] op_sel_hi:[0,1,1] neg_lo:[0,0,1] neg_hi:[0,0,1]
	v_pk_fma_f32 v[4:5], v[50:51], v[16:17], v[4:5] op_sel_hi:[1,0,1] neg_lo:[0,0,1] neg_hi:[0,0,1]
	v_pk_fma_f32 v[6:7], v[32:33], v[16:17], v[6:7] op_sel_hi:[1,0,1] neg_lo:[0,0,1] neg_hi:[0,0,1]
	v_pk_add_f32 v[2:3], v[20:21], v[2:3]
	v_pk_add_f32 v[12:13], v[22:23], v[12:13]
	v_pk_add_f32 v[4:5], v[28:29], v[4:5]
	v_pk_add_f32 v[6:7], v[30:31], v[6:7]
	s_cbranch_scc0 .LBB0_198
	s_and_b32 s48, s53, 3
	ds_write_b128 v42, v[0:3] offset:50176
	ds_write_b128 v42, v[12:15] offset:50240
	ds_write_b128 v42, v[8:11] offset:50304
	ds_write_b128 v42, v[4:7] offset:50368
	s_waitcnt lgkmcnt(0)
	s_barrier
; __device__ __forceinline__ unsigned pk2(float lo, float hi) { return f2bf(lo) | (f2bf(hi) << 16); }
; __device__ __forceinline__ void s5_gen(LAS unsigned char* lds, const S5In P, int g, int q, bf16_t* Bst, bf16_t* Bout, const int tid) {
;     ...
;     { const int di = q >> 1, ri = q & 1;
;       for (int cid = tid; cid < 2048; cid += 512) { const int nl = cid >> 5, k0 = (cid & 31) * 8, r = k0 >> 4, ch0 = k0 & 15;
;         const f32x2v w = pw[(di * 64 + nl) * 17 + (di == 0 ? 15 - r : r)]; float v[8];
; #pragma unroll
;         for (int j = 0; j < 8; ++j) { const f32x2v b = bb[(di * 64 + nl) * 16 + ch0 + j]; const float zr = w.x * b.x - w.y * b.y, zi = w.x * b.y + w.y * b.x; v[j] = (ri == 0 ? zr : zi) * P.gain[g * 16 + ch0 + j]; }
;         u32x4 o; o.x = pk2(v[0], v[1]); o.y = pk2(v[2], v[3]); o.z = pk2(v[4], v[5]); o.w = pk2(v[6], v[7]);
;         *(u32x4*)(Bst + ((size_t)g * 256 + q * 64 + nl) * 256 + k0) = o; } }
	s_and_saveexec_b64 s[28:29], s[38:39]
	s_movk_i32 s51, 0x5ff
	s_mov_b32 s54, 0xffff0000
	s_cbranch_execz .LBB0_202
	v_mbcnt_lo_u32_b32 v43, -1, 0
	v_mbcnt_hi_u32_b32 v43, -1, v43
	v_and_b32_e32 v44, 31, v43
	v_lshrrev_b32_e32 v45, 5, v66
	v_lshrrev_b32_e32 v46, 1, v44
	v_and_b32_e32 v47, 1, v44
	v_lshlrev_b32_e32 v47, 3, v47
	s_lshl_b32 s30, s16, 4
	v_add_u32_e32 v57, s30, v47
	v_lshlrev_b32_e32 v208, 2, v57
	v_lshl_add_u64 v[58:59], s[96:97], 0, v[208:209]
	global_load_dwordx4 v[6:9], v[58:59], off
	global_load_dwordx4 v[10:13], v[58:59], off offset:16
	s_lshr_b32 s42, s48, 1
	s_and_b32 s43, s48, 1
	s_cmp_eq_u32 s43, 0
	s_cselect_b64 s[46:47], -1, 0
	s_lshl_b32 s44, s42, 6
	v_add_u32_e32 v57, s44, v45
	v_xor_b32_e32 v58, 15, v46
	s_cmp_eq_u32 s42, 0
	s_cselect_b64 vcc, -1, 0
	v_cndmask_b32_e32 v58, v46, v58, vcc
	v_mul_u32_u24_e32 v52, 0x88, v57
	v_lshl_add_u32 v52, v58, 3, v52
	v_lshlrev_b32_e32 v53, 7, v57
	v_lshl_add_u32 v53, v47, 3, v53
	v_add_u32_e32 v53, 0x4400, v53
	s_lshl_b32 s45, s16, 8
	s_lshl_b32 s17, s48, 6
	s_add_i32 s45, s45, s17
	v_add_u32_e32 v57, s45, v45
	v_lshlrev_b32_e32 v57, 9, v57
	v_lshl_add_u32 v208, v44, 4, v57
	v_lshl_add_u64 v[48:49], s[18:19], 0, v[208:209]
	s_mov_b64 s[50:51], 0x2000
	s_waitcnt vmcnt(0)
	ds_read_b64 v[4:5], v52
	ds_read_b128 v[14:17], v53
	ds_read_b128 v[18:21], v53 offset:16
	ds_read_b128 v[22:25], v53 offset:32
	ds_read_b128 v[26:29], v53 offset:48
	s_waitcnt lgkmcnt(0)
	v_mul_f32_e32 v30, v5, v15
	v_mul_f32_e32 v31, v5, v14
	v_fma_f32 v30, v4, v14, -v30
	v_fma_f32 v31, v4, v15, v31
	v_cndmask_b32_e64 v14, v31, v30, s[46:47]
	v_mul_f32_e32 v14, v14, v6
	v_mul_f32_e32 v30, v5, v17
	v_mul_f32_e32 v31, v5, v16
	v_fma_f32 v30, v4, v16, -v30
	v_fma_f32 v31, v4, v17, v31
	v_cndmask_b32_e64 v16, v31, v30, s[46:47]
	v_mul_f32_e32 v16, v16, v7
	v_mul_f32_e32 v30, v5, v19
	v_mul_f32_e32 v31, v5, v18
	v_fma_f32 v30, v4, v18, -v30
	v_fma_f32 v31, v4, v19, v31
	v_cndmask_b32_e64 v18, v31, v30, s[46:47]
	v_mul_f32_e32 v18, v18, v8
	v_mul_f32_e32 v30, v5, v21
	v_mul_f32_e32 v31, v5, v20
	v_fma_f32 v30, v4, v20, -v30
	v_fma_f32 v31, v4, v21, v31
	v_cndmask_b32_e64 v20, v31, v30, s[46:47]
	v_mul_f32_e32 v20, v20, v9
	v_mul_f32_e32 v30, v5, v23
	v_mul_f32_e32 v31, v5, v22
	v_fma_f32 v30, v4, v22, -v30
	v_fma_f32 v31, v4, v23, v31
	v_cndmask_b32_e64 v22, v31, v30, s[46:47]
	v_mul_f32_e32 v22, v22, v10
	v_mul_f32_e32 v30, v5, v25
	v_mul_f32_e32 v31, v5, v24
	v_fma_f32 v30, v4, v24, -v30
	v_fma_f32 v31, v4, v25, v31
	v_cndmask_b32_e64 v24, v31, v30, s[46:47]
	v_mul_f32_e32 v24, v24, v11
	v_mul_f32_e32 v30, v5, v27
	v_mul_f32_e32 v31, v5, v26
	v_fma_f32 v30, v4, v26, -v30
	v_fma_f32 v31, v4, v27, v31
	v_cndmask_b32_e64 v26, v31, v30, s[46:47]
	v_mul_f32_e32 v26, v26, v12
	v_mul_f32_e32 v30, v5, v29
	v_mul_f32_e32 v31, v5, v28
	v_fma_f32 v30, v4, v28, -v30
	v_fma_f32 v31, v4, v29, v31
	v_cndmask_b32_e64 v28, v31, v30, s[46:47]
	v_mul_f32_e32 v28, v28, v13
	v_cvt_pk_bf16_f32 v0, v14, v16
	v_cvt_pk_bf16_f32 v1, v18, v20
	v_cvt_pk_bf16_f32 v2, v22, v24
	v_cvt_pk_bf16_f32 v3, v26, v28
	global_store_dwordx4 v[48:49], v[0:3], off
	s_nop 1
	v_lshl_add_u64 v[48:49], v[48:49], 0, s[50:51]
	ds_read_b64 v[4:5], v52 offset:2176
	ds_read_b128 v[14:17], v53 offset:2048
	ds_read_b128 v[18:21], v53 offset:2064
	ds_read_b128 v[22:25], v53 offset:2080
	ds_read_b128 v[26:29], v53 offset:2096
	s_waitcnt lgkmcnt(0)
	v_mul_f32_e32 v30, v5, v15
	v_mul_f32_e32 v31, v5, v14
	v_fma_f32 v30, v4, v14, -v30
	v_fma_f32 v31, v4, v15, v31
	v_cndmask_b32_e64 v14, v31, v30, s[46:47]
	v_mul_f32_e32 v14, v14, v6
	v_mul_f32_e32 v30, v5, v17
	v_mul_f32_e32 v31, v5, v16
	v_fma_f32 v30, v4, v16, -v30
	v_fma_f32 v31, v4, v17, v31
	v_cndmask_b32_e64 v16, v31, v30, s[46:47]
	v_mul_f32_e32 v16, v16, v7
	v_mul_f32_e32 v30, v5, v19
	v_mul_f32_e32 v31, v5, v18
	v_fma_f32 v30, v4, v18, -v30
	v_fma_f32 v31, v4, v19, v31
	v_cndmask_b32_e64 v18, v31, v30, s[46:47]
	v_mul_f32_e32 v18, v18, v8
	v_mul_f32_e32 v30, v5, v21
	v_mul_f32_e32 v31, v5, v20
	v_fma_f32 v30, v4, v20, -v30
	v_fma_f32 v31, v4, v21, v31
	v_cndmask_b32_e64 v20, v31, v30, s[46:47]
	v_mul_f32_e32 v20, v20, v9
	v_mul_f32_e32 v30, v5, v23
	v_mul_f32_e32 v31, v5, v22
	v_fma_f32 v30, v4, v22, -v30
	v_fma_f32 v31, v4, v23, v31
	v_cndmask_b32_e64 v22, v31, v30, s[46:47]
	v_mul_f32_e32 v22, v22, v10
	v_mul_f32_e32 v30, v5, v25
	v_mul_f32_e32 v31, v5, v24
	v_fma_f32 v30, v4, v24, -v30
	v_fma_f32 v31, v4, v25, v31
	v_cndmask_b32_e64 v24, v31, v30, s[46:47]
	v_mul_f32_e32 v24, v24, v11
	v_mul_f32_e32 v30, v5, v27
	v_mul_f32_e32 v31, v5, v26
	v_fma_f32 v30, v4, v26, -v30
	v_fma_f32 v31, v4, v27, v31
	v_cndmask_b32_e64 v26, v31, v30, s[46:47]
	v_mul_f32_e32 v26, v26, v12
	v_mul_f32_e32 v30, v5, v29
	v_mul_f32_e32 v31, v5, v28
	v_fma_f32 v30, v4, v28, -v30
	v_fma_f32 v31, v4, v29, v31
	v_cndmask_b32_e64 v28, v31, v30, s[46:47]
	v_mul_f32_e32 v28, v28, v13
	v_cvt_pk_bf16_f32 v0, v14, v16
	v_cvt_pk_bf16_f32 v1, v18, v20
	v_cvt_pk_bf16_f32 v2, v22, v24
	v_cvt_pk_bf16_f32 v3, v26, v28
	global_store_dwordx4 v[48:49], v[0:3], off
	s_nop 1
	v_lshl_add_u64 v[48:49], v[48:49], 0, s[50:51]
	ds_read_b64 v[4:5], v52 offset:4352
	ds_read_b128 v[14:17], v53 offset:4096
	ds_read_b128 v[18:21], v53 offset:4112
	ds_read_b128 v[22:25], v53 offset:4128
	ds_read_b128 v[26:29], v53 offset:4144
	s_waitcnt lgkmcnt(0)
; __device__ __forceinline__ unsigned pk2(float lo, float hi) { return f2bf(lo) | (f2bf(hi) << 16); }
; __device__ __forceinline__ void s5_gen(LAS unsigned char* lds, const S5In P, int g, int q, bf16_t* Bst, bf16_t* Bout, const int tid) {
;     ...
;       for (int cid = tid; cid < 2048; cid += 512) { const int nl = cid >> 5, k0 = (cid & 31) * 8, r = k0 >> 4, ch0 = k0 & 15;
;         const f32x2v w = pw[(di * 64 + nl) * 17 + (di == 0 ? 15 - r : r)]; float v[8];
; #pragma unroll
;         for (int j = 0; j < 8; ++j) { const f32x2v b = bb[(di * 64 + nl) * 16 + ch0 + j]; const float zr = w.x * b.x - w.y * b.y, zi = w.x * b.y + w.y * b.x; v[j] = (ri == 0 ? zr : zi) * P.gain[g * 16 + ch0 + j]; }
;         u32x4 o; o.x = pk2(v[0], v[1]); o.y = pk2(v[2], v[3]); o.z = pk2(v[4], v[5]); o.w = pk2(v[6], v[7]);
;         *(u32x4*)(Bst + ((size_t)g * 256 + q * 64 + nl) * 256 + k0) = o; } }
	v_mul_f32_e32 v30, v5, v15
	v_mul_f32_e32 v31, v5, v14
	v_fma_f32 v30, v4, v14, -v30
	v_fma_f32 v31, v4, v15, v31
	v_cndmask_b32_e64 v14, v31, v30, s[46:47]
	v_mul_f32_e32 v14, v14, v6
	v_mul_f32_e32 v30, v5, v17
	v_mul_f32_e32 v31, v5, v16
	v_fma_f32 v30, v4, v16, -v30
	v_fma_f32 v31, v4, v17, v31
	v_cndmask_b32_e64 v16, v31, v30, s[46:47]
	v_mul_f32_e32 v16, v16, v7
	v_mul_f32_e32 v30, v5, v19
	v_mul_f32_e32 v31, v5, v18
	v_fma_f32 v30, v4, v18, -v30
	v_fma_f32 v31, v4, v19, v31
	v_cndmask_b32_e64 v18, v31, v30, s[46:47]
	v_mul_f32_e32 v18, v18, v8
	v_mul_f32_e32 v30, v5, v21
	v_mul_f32_e32 v31, v5, v20
	v_fma_f32 v30, v4, v20, -v30
	v_fma_f32 v31, v4, v21, v31
	v_cndmask_b32_e64 v20, v31, v30, s[46:47]
	v_mul_f32_e32 v20, v20, v9
	v_mul_f32_e32 v30, v5, v23
	v_mul_f32_e32 v31, v5, v22
	v_fma_f32 v30, v4, v22, -v30
	v_fma_f32 v31, v4, v23, v31
	v_cndmask_b32_e64 v22, v31, v30, s[46:47]
	v_mul_f32_e32 v22, v22, v10
	v_mul_f32_e32 v30, v5, v25
	v_mul_f32_e32 v31, v5, v24
	v_fma_f32 v30, v4, v24, -v30
	v_fma_f32 v31, v4, v25, v31
	v_cndmask_b32_e64 v24, v31, v30, s[46:47]
	v_mul_f32_e32 v24, v24, v11
	v_mul_f32_e32 v30, v5, v27
	v_mul_f32_e32 v31, v5, v26
	v_fma_f32 v30, v4, v26, -v30
	v_fma_f32 v31, v4, v27, v31
	v_cndmask_b32_e64 v26, v31, v30, s[46:47]
	v_mul_f32_e32 v26, v26, v12
	v_mul_f32_e32 v30, v5, v29
	v_mul_f32_e32 v31, v5, v28
	v_fma_f32 v30, v4, v28, -v30
	v_fma_f32 v31, v4, v29, v31
	v_cndmask_b32_e64 v28, v31, v30, s[46:47]
	v_mul_f32_e32 v28, v28, v13
	v_cvt_pk_bf16_f32 v0, v14, v16
	v_cvt_pk_bf16_f32 v1, v18, v20
	v_cvt_pk_bf16_f32 v2, v22, v24
	v_cvt_pk_bf16_f32 v3, v26, v28
	global_store_dwordx4 v[48:49], v[0:3], off
	s_nop 1
	v_lshl_add_u64 v[48:49], v[48:49], 0, s[50:51]
	ds_read_b64 v[4:5], v52 offset:6528
	ds_read_b128 v[14:17], v53 offset:6144
	ds_read_b128 v[18:21], v53 offset:6160
	ds_read_b128 v[22:25], v53 offset:6176
	ds_read_b128 v[26:29], v53 offset:6192
	s_waitcnt lgkmcnt(0)
	v_mul_f32_e32 v30, v5, v15
	v_mul_f32_e32 v31, v5, v14
	v_fma_f32 v30, v4, v14, -v30
	v_fma_f32 v31, v4, v15, v31
	v_cndmask_b32_e64 v14, v31, v30, s[46:47]
	v_mul_f32_e32 v14, v14, v6
	v_mul_f32_e32 v30, v5, v17
	v_mul_f32_e32 v31, v5, v16
	v_fma_f32 v30, v4, v16, -v30
	v_fma_f32 v31, v4, v17, v31
	v_cndmask_b32_e64 v16, v31, v30, s[46:47]
	v_mul_f32_e32 v16, v16, v7
	v_mul_f32_e32 v30, v5, v19
	v_mul_f32_e32 v31, v5, v18
	v_fma_f32 v30, v4, v18, -v30
	v_fma_f32 v31, v4, v19, v31
	v_cndmask_b32_e64 v18, v31, v30, s[46:47]
	v_mul_f32_e32 v18, v18, v8
	v_mul_f32_e32 v30, v5, v21
	v_mul_f32_e32 v31, v5, v20
	v_fma_f32 v30, v4, v20, -v30
	v_fma_f32 v31, v4, v21, v31
	v_cndmask_b32_e64 v20, v31, v30, s[46:47]
	v_mul_f32_e32 v20, v20, v9
	v_mul_f32_e32 v30, v5, v23
	v_mul_f32_e32 v31, v5, v22
	v_fma_f32 v30, v4, v22, -v30
	v_fma_f32 v31, v4, v23, v31
	v_cndmask_b32_e64 v22, v31, v30, s[46:47]
	v_mul_f32_e32 v22, v22, v10
	v_mul_f32_e32 v30, v5, v25
	v_mul_f32_e32 v31, v5, v24
	v_fma_f32 v30, v4, v24, -v30
	v_fma_f32 v31, v4, v25, v31
	v_cndmask_b32_e64 v24, v31, v30, s[46:47]
	v_mul_f32_e32 v24, v24, v11
	v_mul_f32_e32 v30, v5, v27
	v_mul_f32_e32 v31, v5, v26
	v_fma_f32 v30, v4, v26, -v30
	v_fma_f32 v31, v4, v27, v31
	v_cndmask_b32_e64 v26, v31, v30, s[46:47]
	v_mul_f32_e32 v26, v26, v12
	v_mul_f32_e32 v30, v5, v29
	v_mul_f32_e32 v31, v5, v28
	v_fma_f32 v30, v4, v28, -v30
	v_fma_f32 v31, v4, v29, v31
	v_cndmask_b32_e64 v28, v31, v30, s[46:47]
	v_mul_f32_e32 v28, v28, v13
	v_cvt_pk_bf16_f32 v0, v14, v16
	v_cvt_pk_bf16_f32 v1, v18, v20
	v_cvt_pk_bf16_f32 v2, v22, v24
	v_cvt_pk_bf16_f32 v3, v26, v28
	global_store_dwordx4 v[48:49], v[0:3], off
	s_nop 1
